# attention V tile staged with conflict-free transposed LDS writes; FFN weight transposes moved behind the attention queue on the non-scan workgroups
# speedup vs baseline: 1.0020x; 1.0020x over previous
.LBB0_517:
	s_mov_b32 s99, 0
	s_add_u32 s34, s16, 0x6d00000
	s_addc_u32 s35, s17, 0
	s_add_u32 s36, s16, 0x800000
	s_addc_u32 s37, s17, 0
	s_add_u32 s56, s16, 0x5d00000
	s_addc_u32 s57, s17, 0
	s_add_u32 s42, s16, 0x8d00000
	s_addc_u32 s43, s17, 0
	s_add_u32 s44, s16, 0xa500000
	s_addc_u32 s45, s17, 0
	s_add_u32 s46, s16, 0xfd00000
	s_addc_u32 s47, s17, 0
	s_add_u32 s6, s30, s28
	s_addc_u32 s7, s31, s29
	s_add_u32 s28, s6, 0xfd01000
	s_addc_u32 s29, s7, 0
	s_add_u32 s30, s6, 0xa520000
	s_addc_u32 s31, s7, 0
	s_add_i32 s58, 0, 0x20000
	s_mov_b32 s15, 0
	v_cmp_eq_u32_e64 s[4:5], 0, v154
	v_mov_b32_e32 v101, 0
	v_mov_b32_e32 v110, s58
	s_movk_i32 s59, 0x2ff
	s_mov_b32 s60, 0xc2fc0000
	s_mov_b32 s61, 0x800000
	s_movk_i32 s62, 0x7f
	s_mov_b64 s[48:49], 0x1000
	s_movk_i32 s63, 0x1000
	s_movk_i32 s64, 0xff
	s_movk_i32 s65, 0x68
	s_movk_i32 s66, 0x600
	s_movk_i32 s67, 0x100
	s_movk_i32 s68, 0x48
	s_mov_b32 s69, 0xf149f2ca
	s_mov_b32 s70, 0x3e16c740
	s_mov_b64 s[50:51], 0x20000
	v_mov_b32_e32 v111, 0x42800000
	v_mov_b32_e32 v112, 0x42000000
	v_not_b32_e32 v113, 63
	v_mov_b32_e32 v114, 0x80
	v_mov_b32_e32 v115, 0xf149f2ca
	v_mbcnt_hi_u32_b32 v153, -1, v153
	s_branch .LBB0_521

.LBB0_521:
	s_barrier
	s_and_saveexec_b64 s[6:7], s[4:5]
	s_cbranch_execz .LBB0_525
	s_mov_b64 s[10:11], exec
	s_waitcnt vmcnt(16)
	v_mbcnt_lo_u32_b32 v0, s10, 0
	v_mbcnt_hi_u32_b32 v0, s11, v0
	v_cmp_eq_u32_e32 vcc, 0, v0
	s_and_saveexec_b64 s[8:9], vcc
	s_cbranch_execz .LBB0_524
	s_bcnt1_i32_b64 s10, s[10:11]
	s_waitcnt vmcnt(15)
	v_mov_b32_e32 v1, s10
	s_cmp_eq_u32 s99, 0
	s_cbranch_scc1 .Lxp0_noinc
	global_atomic_add v101, v1, s[16:17] offset:768
.Lxp0_noinc:
	global_atomic_add v1, v101, v1, s[16:17] offset:256 sc0

.LBB0_525:
	s_or_b64 exec, exec, s[6:7]
	s_waitcnt lgkmcnt(0)
	s_barrier
	s_waitcnt vmcnt(16)
	ds_read_b32 v0, v110
	s_mov_b64 s[6:7], -1
	s_waitcnt lgkmcnt(0)
	v_cmp_lt_i32_e32 vcc, s59, v0
	v_readfirstlane_b32 s52, v0
	s_cbranch_vccnz .LBB0_520
	s_mov_b32 s99, 1
	s_cmpk_gt_i32 s52, 0x1ff
	s_cbranch_scc0 .LBB0_536
	s_and_b32 s8, s52, 3
	v_cvt_f32_ubyte0_e32 v0, s8
	v_sub_f32_e32 v0, 0xc0a00000, v0
	v_cmp_gt_f32_e32 vcc, s60, v0
	s_bfe_u32 s9, s52, 0x20002
	s_and_b64 s[6:7], vcc, exec
	s_waitcnt vmcnt(15)
	v_cndmask_b32_e32 v1, 0, v111, vcc
	v_add_f32_e32 v0, v0, v1
	v_exp_f32_e32 v0, v0
	s_cselect_b32 s6, 0xffffffc0, 0
	v_mov_b32_e32 v36, v152
	v_ldexp_f32 v0, v0, s6
	s_waitcnt vmcnt(0)
	v_sub_f32_e32 v16, 1.0, v0
	v_cmp_gt_f32_e32 vcc, s61, v16
	s_and_b64 s[6:7], vcc, exec
	s_cselect_b32 s11, 32, 0
	s_lshl_b32 s6, s52, 4
	s_and_b32 s10, s6, 0x7fffff00
	v_ashrrev_i32_e32 v0, 1, v36
	s_addk_i32 s10, 0xe000
	v_and_b32_e32 v80, 0xffffffe0, v0
	v_and_b32_e32 v92, 31, v36
	v_add_u32_e32 v37, s10, v80
	v_or_b32_e32 v0, v37, v92
	s_lshl_b32 s14, s9, 12
	v_ashrrev_i32_e32 v1, 31, v0
	v_lshl_add_u64 v[8:9], v[0:1], 0, s[14:15]
	v_bfe_u32 v93, v36, 5, 1
	v_lshlrev_b64 v[0:1], 7, v[8:9]
	v_lshl_add_u64 v[2:3], s[20:21], 0, v[0:1]
	v_lshlrev_b32_e32 v4, 5, v93
	v_mov_b32_e32 v5, v101
	v_lshl_add_u64 v[0:1], s[22:23], 0, v[0:1]
	v_lshlrev_b64 v[8:9], 11, v[8:9]
	v_lshl_add_u64 v[28:29], v[0:1], 0, v[4:5]
	v_lshl_add_u64 v[8:9], s[34:35], 0, v[8:9]
	s_lshl_b32 s6, s8, 7
	s_mov_b32 s7, s15
	v_lshl_add_u64 v[26:27], v[2:3], 0, v[4:5]
	global_load_dwordx4 v[0:3], v[28:29], off
	global_load_dwordx4 v[4:7], v[26:27], off
	v_lshl_add_u64 v[8:9], v[8:9], 0, s[6:7]
	v_lshlrev_b32_e32 v100, 4, v93
	v_lshl_add_u64 v[30:31], v[8:9], 0, v[100:101]
	global_load_dwordx4 v[8:11], v[30:31], off
	global_load_dwordx4 v[12:15], v[30:31], off offset:64
	global_load_dwordx4 v[18:21], v[28:29], off offset:16
	global_load_dwordx4 v[22:25], v[26:27], off offset:16
	v_ldexp_f32 v16, v16, s11
	v_log_f32_e32 v16, v16
	v_bitop3_b32 v32, v37, s62, v92 bitop3:0xc8
	v_cndmask_b32_e32 v17, 0, v112, vcc
	v_add_u32_e32 v32, 1, v32
	v_sub_f32_e32 v81, v16, v17
	v_cvt_f32_ubyte0_e32 v16, v32
	v_mul_f32_e32 v17, v81, v16
	v_cmp_gt_f32_e32 vcc, s60, v17
	s_lshl_b32 s7, s9, 7
	s_lshl_b32 s9, s8, 5
	v_cndmask_b32_e32 v17, 0, v111, vcc
	v_fmac_f32_e32 v17, v81, v16
	v_exp_f32_e32 v16, v17
	v_cndmask_b32_e32 v17, 0, v113, vcc
	v_ashrrev_i32_e32 v94, 7, v37
	s_or_b32 s7, s7, s9
	v_ldexp_f32 v46, v16, v17
	s_lshl_b32 s11, s8, 6
	s_add_u32 s6, s34, s6
	v_or_b32_e32 v96, 31, v37
	v_mul_u32_u24_e32 v37, 0x68, v92
	s_mov_b32 s53, 0
	s_mov_b32 s54, s10
	s_waitcnt vmcnt(5)
	v_mov_b32_e32 v16, v0
	v_mov_b32_e32 v33, v0
	s_waitcnt vmcnt(4)
	v_mov_b32_e32 v0, v5
	s_waitcnt vmcnt(3)
	v_and_b32_e32 v43, 0xffff0000, v8
	s_waitcnt vmcnt(2)
	v_and_b32_e32 v42, 0xffff0000, v12
	v_mov_b32_e32 v17, v4
	v_mov_b32_e32 v32, v4
	v_mov_b32_e32 v4, v1
	v_mov_b32_e32 v34, v2
	v_mov_b32_e32 v35, v6
	v_mov_b32_e32 v38, v6
	v_mov_b32_e32 v6, v3
	v_lshlrev_b32_e32 v41, 16, v8
	v_lshlrev_b32_e32 v40, 16, v12
	v_lshlrev_b32_e32 v45, 16, v9
	v_lshlrev_b32_e32 v44, 16, v13
	v_and_b32_e32 v9, 0xffff0000, v9
	v_and_b32_e32 v8, 0xffff0000, v13
	v_pk_mul_f32 v[0:1], v[0:1], v[42:43]
	v_mov_b32_e32 v39, v2
	v_mov_b32_e32 v2, v7
	v_pk_mul_f32 v[12:13], v[16:17], v[40:41]
	v_pk_mul_f32 v[16:17], v[32:33], v[40:41]
	v_pk_mul_f32 v[4:5], v[4:5], v[42:43]
	v_pk_mul_f32 v[32:33], v[34:35], v[44:45]
	v_pk_mul_f32 v[6:7], v[6:7], v[8:9]
	v_add_f32_e32 v0, v0, v1
	v_pk_mul_f32 v[34:35], v[38:39], v[44:45]
	v_pk_mul_f32 v[2:3], v[2:3], v[8:9]
	v_sub_f32_e32 v8, v13, v12
	v_add_f32_e32 v9, v16, v17
	v_sub_f32_e32 v4, v5, v4
	v_sub_f32_e32 v1, v33, v32
	v_sub_f32_e32 v6, v7, v6
	v_cvt_pk_bf16_f32 v64, v8, v4
	v_cvt_pk_bf16_f32 v68, v9, v0
	v_mul_f32_e32 v0, v0, v46
	v_add_f32_e32 v5, v34, v35
	v_add_f32_e32 v2, v2, v3
	v_mul_f32_e32 v3, v8, v46
	v_mul_f32_e32 v4, v4, v46
	v_mul_f32_e32 v7, v9, v46
	v_cvt_pk_bf16_f32 v16, v3, v4
	v_cvt_pk_bf16_f32 v32, v7, v0
	v_cvt_pk_bf16_f32 v65, v1, v6
	v_mul_f32_e32 v0, v1, v46
	v_mul_f32_e32 v1, v6, v46
	v_cvt_pk_bf16_f32 v69, v5, v2
	v_cvt_pk_bf16_f32 v17, v0, v1
	v_mul_f32_e32 v0, v5, v46
	v_mul_f32_e32 v1, v2, v46
	v_cvt_pk_bf16_f32 v33, v0, v1
	v_lshlrev_b32_e32 v1, 16, v10
	v_lshlrev_b32_e32 v0, 16, v14
	s_waitcnt vmcnt(1)
	v_mov_b32_e32 v2, v18
	s_waitcnt vmcnt(0)
	v_mov_b32_e32 v3, v22
	v_pk_mul_f32 v[2:3], v[2:3], v[0:1]
	s_nop 0
	v_sub_f32_e32 v4, v3, v2
	v_mov_b32_e32 v2, v22
	v_mov_b32_e32 v3, v18
	v_pk_mul_f32 v[0:1], v[2:3], v[0:1]
	v_mov_b32_e32 v22, v19
	v_add_f32_e32 v5, v0, v1
	v_and_b32_e32 v1, 0xffff0000, v10
	v_and_b32_e32 v0, 0xffff0000, v14
	v_mov_b32_e32 v18, v23
	v_pk_mul_f32 v[2:3], v[22:23], v[0:1]
	v_pk_mul_f32 v[0:1], v[18:19], v[0:1]
	v_sub_f32_e32 v2, v3, v2
	v_add_f32_e32 v0, v0, v1
	v_mul_f32_e32 v1, v46, v4
	v_cvt_pk_bf16_f32 v66, v4, v2
	v_cvt_pk_bf16_f32 v70, v5, v0
	v_mul_f32_e32 v2, v46, v2
	v_cvt_pk_bf16_f32 v18, v1, v2
	v_mul_f32_e32 v1, v46, v5
	v_mul_f32_e32 v0, v46, v0
	v_cvt_pk_bf16_f32 v34, v1, v0
	v_lshlrev_b32_e32 v1, 16, v11
	v_lshlrev_b32_e32 v0, 16, v15
	v_mov_b32_e32 v2, v20
	v_mov_b32_e32 v3, v24
	v_pk_mul_f32 v[2:3], v[2:3], v[0:1]
	s_nop 0
	v_sub_f32_e32 v4, v3, v2
	v_mov_b32_e32 v2, v24
	v_mov_b32_e32 v3, v20
	v_pk_mul_f32 v[0:1], v[2:3], v[0:1]
	v_mov_b32_e32 v24, v21
	v_add_f32_e32 v5, v0, v1
	v_and_b32_e32 v1, 0xffff0000, v11
	v_and_b32_e32 v0, 0xffff0000, v15
	v_mov_b32_e32 v20, v25
	v_pk_mul_f32 v[2:3], v[24:25], v[0:1]
	v_pk_mul_f32 v[0:1], v[20:21], v[0:1]
	v_sub_f32_e32 v2, v3, v2
	v_add_f32_e32 v0, v0, v1
	v_mul_f32_e32 v1, v46, v4
	v_cvt_pk_bf16_f32 v67, v4, v2
	v_cvt_pk_bf16_f32 v71, v5, v0
	v_mul_f32_e32 v2, v46, v2
	v_cvt_pk_bf16_f32 v19, v1, v2
	v_mul_f32_e32 v1, v46, v5
	v_mul_f32_e32 v0, v46, v0
	v_cvt_pk_bf16_f32 v35, v1, v0
	global_load_dwordx4 v[0:3], v[30:31], off offset:32
	global_load_dwordx4 v[4:7], v[30:31], off offset:96
	global_load_dwordx4 v[8:11], v[28:29], off offset:64
	global_load_dwordx4 v[12:15], v[26:27], off offset:64
	global_load_dwordx4 v[20:23], v[28:29], off offset:80
	s_nop 0
	global_load_dwordx4 v[24:27], v[26:27], off offset:80
	s_waitcnt vmcnt(5)
	v_lshlrev_b32_e32 v29, 16, v0
	s_waitcnt vmcnt(4)
	v_lshlrev_b32_e32 v28, 16, v4
	s_waitcnt vmcnt(3)
	v_mov_b32_e32 v30, v8
	s_waitcnt vmcnt(2)
	v_mov_b32_e32 v31, v12
	v_mov_b32_e32 v38, v12
	v_and_b32_e32 v41, 0xffff0000, v0
	v_and_b32_e32 v40, 0xffff0000, v4
	v_mov_b32_e32 v12, v9
	v_mov_b32_e32 v39, v8
	v_mov_b32_e32 v8, v13
	v_pk_mul_f32 v[30:31], v[30:31], v[28:29]
	v_pk_mul_f32 v[12:13], v[12:13], v[40:41]
	v_pk_mul_f32 v[28:29], v[38:39], v[28:29]
	v_pk_mul_f32 v[8:9], v[8:9], v[40:41]
	v_sub_f32_e32 v0, v31, v30
	v_sub_f32_e32 v12, v13, v12
	v_add_f32_e32 v4, v28, v29
	v_add_f32_e32 v8, v8, v9
	v_cvt_pk_bf16_f32 v72, v0, v12
	v_mul_f32_e32 v0, v46, v0
	v_mul_f32_e32 v9, v46, v12
	v_cvt_pk_bf16_f32 v76, v4, v8
	v_cvt_pk_bf16_f32 v38, v0, v9
	v_mul_f32_e32 v0, v46, v4
	v_mul_f32_e32 v4, v46, v8
	v_lshlrev_b32_e32 v9, 16, v1
	v_lshlrev_b32_e32 v8, 16, v5
	v_mov_b32_e32 v12, v10
	v_mov_b32_e32 v13, v14
	v_pk_mul_f32 v[12:13], v[12:13], v[8:9]
	v_cvt_pk_bf16_f32 v42, v0, v4
	v_and_b32_e32 v1, 0xffff0000, v1
	v_sub_f32_e32 v28, v13, v12
	v_mov_b32_e32 v12, v14
	v_mov_b32_e32 v13, v10
	v_and_b32_e32 v0, 0xffff0000, v5
	v_mov_b32_e32 v14, v11
	v_mov_b32_e32 v10, v15
	v_pk_mul_f32 v[8:9], v[12:13], v[8:9]
	v_pk_mul_f32 v[4:5], v[14:15], v[0:1]
	v_pk_mul_f32 v[0:1], v[10:11], v[0:1]
	v_add_f32_e32 v8, v8, v9
	v_sub_f32_e32 v4, v5, v4
	v_add_f32_e32 v0, v0, v1
	v_mul_f32_e32 v1, v46, v28
	v_cvt_pk_bf16_f32 v73, v28, v4
	v_cvt_pk_bf16_f32 v77, v8, v0
	v_mul_f32_e32 v4, v46, v4
	v_cvt_pk_bf16_f32 v39, v1, v4
	v_mul_f32_e32 v1, v46, v8
	v_mul_f32_e32 v0, v46, v0
	v_cvt_pk_bf16_f32 v43, v1, v0
	v_lshlrev_b32_e32 v1, 16, v2
	v_lshlrev_b32_e32 v0, 16, v6
	s_waitcnt vmcnt(1)
	v_mov_b32_e32 v4, v20
	s_waitcnt vmcnt(0)
	v_mov_b32_e32 v5, v24
	v_pk_mul_f32 v[4:5], v[4:5], v[0:1]
	s_nop 0
	v_sub_f32_e32 v8, v5, v4
	v_mov_b32_e32 v4, v24
	v_mov_b32_e32 v5, v20
	v_pk_mul_f32 v[0:1], v[4:5], v[0:1]
	v_mov_b32_e32 v24, v21
	v_add_f32_e32 v9, v0, v1
	v_and_b32_e32 v1, 0xffff0000, v2
	v_and_b32_e32 v0, 0xffff0000, v6
	v_mov_b32_e32 v20, v25
	v_pk_mul_f32 v[4:5], v[24:25], v[0:1]
	v_pk_mul_f32 v[0:1], v[20:21], v[0:1]
	v_sub_f32_e32 v2, v5, v4
	v_add_f32_e32 v0, v0, v1
	v_mul_f32_e32 v1, v46, v8
	v_cvt_pk_bf16_f32 v74, v8, v2
	v_cvt_pk_bf16_f32 v78, v9, v0
	v_mul_f32_e32 v2, v46, v2
	v_cvt_pk_bf16_f32 v40, v1, v2
	v_mul_f32_e32 v1, v46, v9
	v_mul_f32_e32 v0, v46, v0
	v_cvt_pk_bf16_f32 v44, v1, v0
	v_lshlrev_b32_e32 v1, 16, v3
	v_lshlrev_b32_e32 v0, 16, v7
	v_mov_b32_e32 v4, v22
	v_mov_b32_e32 v5, v26
	v_pk_mul_f32 v[4:5], v[4:5], v[0:1]
	s_nop 0
	v_sub_f32_e32 v6, v5, v4
	v_mov_b32_e32 v4, v26
	v_mov_b32_e32 v5, v22
	v_pk_mul_f32 v[0:1], v[4:5], v[0:1]
	v_mov_b32_e32 v26, v23
	v_add_f32_e32 v4, v0, v1
	v_and_b32_e32 v1, 0xffff0000, v3
	v_and_b32_e32 v0, 0xffff0000, v7
	v_mov_b32_e32 v22, v27
	v_pk_mul_f32 v[2:3], v[26:27], v[0:1]
	v_pk_mul_f32 v[0:1], v[22:23], v[0:1]
	v_sub_f32_e32 v2, v3, v2
	v_add_f32_e32 v0, v0, v1
	v_cvt_pk_bf16_f32 v75, v6, v2
	v_cvt_pk_bf16_f32 v79, v4, v0
	v_mul_f32_e32 v1, v46, v6
	v_mul_f32_e32 v0, v46, v0
	v_mul_f32_e32 v2, v46, v2
	v_cvt_pk_bf16_f32 v41, v1, v2
	v_mul_f32_e32 v1, v46, v4
	v_cvt_pk_bf16_f32 v45, v1, v0
	v_add_u32_e32 v0, s7, v94
	v_ashrrev_i32_e32 v1, 31, v0
	v_lshlrev_b64 v[0:1], 13, v[0:1]
	v_lshl_add_u64 v[0:1], s[36:37], 0, v[0:1]
	v_lshlrev_b32_e32 v2, 7, v92
	v_mov_b32_e32 v3, v101
	v_lshl_add_u64 v[0:1], v[0:1], 0, v[2:3]
	v_lshl_add_u64 v[62:63], v[0:1], 0, v[100:101]
	global_load_dwordx4 v[0:3], v[62:63], off
	v_add_co_u32_e32 v4, vcc, s63, v62
	v_lshl_add_u64 v[82:83], v[62:63], 0, s[48:49]
	s_nop 0
	v_addc_co_u32_e32 v5, vcc, 0, v63, vcc
	global_load_dwordx4 v[20:23], v[4:5], off
	global_load_dwordx4 v[46:49], v[62:63], off offset:32
	global_load_dwordx4 v[50:53], v[82:83], off offset:32
	global_load_dwordx4 v[54:57], v[82:83], off offset:96
	s_waitcnt vmcnt(4)
	v_mfma_f32_32x32x16_bf16 v[0:15], v[16:19], v[0:3], 0
	global_load_dwordx4 v[58:61], v[62:63], off offset:64
	s_addc_u32 s7, s35, 0
	v_cmp_lt_i32_e32 vcc, s64, v36
	s_waitcnt vmcnt(4)
	v_mfma_f32_32x32x16_bf16 v[16:31], v[16:19], v[20:23], 0
	s_waitcnt vmcnt(3)
	v_mfma_f32_32x32x16_bf16 v[0:15], v[38:41], v[46:49], v[0:15]
	global_load_dwordx4 v[46:49], v[82:83], off offset:64
	s_waitcnt vmcnt(3)
	v_mfma_f32_32x32x16_bf16 v[16:31], v[38:41], v[50:53], v[16:31]
	global_load_dwordx4 v[38:41], v[62:63], off offset:96
	s_waitcnt vmcnt(2)
	v_mfma_f32_32x32x16_bf16 v[0:15], v[32:35], v[58:61], v[0:15]
	s_waitcnt vmcnt(1)
	v_mfma_f32_32x32x16_bf16 v[16:31], v[32:35], v[46:49], v[16:31]
	v_bfe_u32 v35, v36, 2, 6
	v_mov_b32_e32 v33, v101
	v_lshlrev_b32_e32 v34, 3, v93
	v_or_b32_e32 v98, s14, v35
	s_waitcnt vmcnt(0)
	v_mfma_f32_32x32x16_bf16 v[0:15], v[42:45], v[38:41], v[0:15]
	v_and_b32_e32 v38, 3, v36
	v_lshlrev_b32_e32 v100, 4, v38
	v_lshlrev_b32_e32 v39, 3, v38
	v_lshlrev_b32_e32 v32, 5, v38
	v_mul_u32_u24_e32 v40, 0x68, v35
	v_add_lshl_u32 v95, v40, v39, 1
	v_lshl_add_u64 v[86:87], s[6:7], 0, v[32:33]
	v_mfma_f32_32x32x16_bf16 v[16:31], v[42:45], v[54:57], v[16:31]
	v_lshl_add_u64 v[88:89], s[6:7], 0, v[100:101]
	s_add_i32 s6, s10, s14
	v_lshl_add_u32 v36, v35, 1, 0
	v_lshl_add_u64 v[82:83], s[20:21], 0, v[32:33]
	v_lshl_add_u64 v[84:85], s[22:23], 0, v[32:33]
	v_add_u32_e32 v39, 64, v95
	v_mul_i32_i24_e32 v40, -4, v93
	v_add_u32_e32 v41, 0, v34
	v_mul_u32_u24_e32 v38, 0x900, v38
	v_add_lshl_u32 v34, v34, v37, 1
	v_mul_u32_u24_e32 v37, 0x90, v92
	v_or_b32_e32 v32, s6, v35
	v_add3_u32 v97, v40, v80, v92
	v_lshlrev_b32_e32 v90, 10, v32
	v_add_u32_e32 v99, v36, v38
	v_add_u32_e32 v102, 0, v39
	v_add_u32_e32 v103, 0, v34
	v_add_u32_e32 v104, v41, v37
	s_branch .LBB0_529

.LBB0_561:
	s_cmp_lt_u32 s2, 64
	s_cbranch_scc1 .Lxp0_end
	v_cmp_eq_u32_e32 vcc, 0, v152
	s_mov_b32 s98, 0x8000
	s_and_saveexec_b64 s[6:7], vcc
	s_cbranch_execz .Lxp0_wdone
.Lxp0_wloop:
	global_load_dword v0, v101, s[16:17] offset:768 sc1
	s_waitcnt vmcnt(0)
	v_cmp_gt_u32_e32 vcc, 0x300, v0
	s_cbranch_vccz .Lxp0_wdone
	s_sub_u32 s98, s98, 1
	s_cmp_eq_u32 s98, 0
	s_cbranch_scc1 .Lxp0_wdone
	s_sleep 8
	s_branch .Lxp0_wloop
.Lxp0_wdone:
	s_or_b64 exec, exec, s[6:7]
	s_barrier
	s_mov_b32 s10, 0
	s_mov_b32 s11, 0
	s_load_dwordx2 s[14:15], s[0:1], 0xe0
	v_mov_b32_e32 v23, v152
	v_and_b32_e32 v22, 63, v23
	v_lshlrev_b32_e32 v8, 3, v22
	v_readfirstlane_b32 s4, v23
	s_ashr_i32 s26, s4, 6
	s_sub_u32 s5, s2, 64
	s_lshl_b32 s5, s5, 3
	s_add_i32 s6, s5, s26
	s_sub_u32 s4, s38, 64
	s_lshl_b32 s8, s4, 3
	s_mov_b32 s16, s0
	s_mov_b32 s17, s1
	s_waitcnt lgkmcnt(0)
	s_cmpk_gt_i32 s6, 0x107f
	s_cbranch_scc1 .Lxp0_end
	s_waitcnt lgkmcnt(0)
	s_add_u32 s10, s14, s10
	s_load_dwordx4 s[20:23], s[16:17], 0xc0
	s_addc_u32 s11, s15, s11
	s_lshl_b32 s4, s26, 14
	v_lshlrev_b32_e32 v0, 2, v23
	v_mov_b32_e32 v1, 0
	v_and_b32_e32 v4, 56, v8
	s_add_i32 s4, s4, 0
	s_waitcnt vmcnt(6)
	v_lshrrev_b32_e32 v10, 5, v22
	v_and_b32_e32 v0, 0x7c, v0
	s_waitcnt vmcnt(5)
	v_lshrrev_b32_e32 v11, 3, v22
	v_mul_u32_u24_e32 v6, 0x84, v4
	v_lshlrev_b32_e32 v4, 1, v4
	v_mov_b32_e32 v5, v1
	s_waitcnt vmcnt(0)
	v_add_u32_e32 v16, s4, v0
	v_mul_u32_u24_e32 v17, 0x84, v10
	v_lshl_add_u64 v[8:9], s[10:11], 0, v[4:5]
	s_mov_b64 s[10:11], 0xb000000
	v_lshlrev_b32_e32 v7, 2, v11
	v_lshl_add_u64 v[4:5], v[8:9], 0, s[10:11]
	v_add3_u32 v12, s4, v6, v7
	s_mov_b64 s[10:11], 0xa500000
	s_lshl_b32 s4, s6, 1
	v_add_u32_e32 v16, v16, v17
	s_mov_b32 s5, 0
	s_waitcnt lgkmcnt(0)
	v_lshl_add_u64 v[2:3], s[22:23], 0, v[0:1]
	v_or_b32_e32 v13, 8, v11
	v_or_b32_e32 v14, 16, v11
	v_or_b32_e32 v15, 24, v11
	v_lshl_add_u64 v[6:7], s[20:21], 0, v[0:1]
	v_lshl_add_u64 v[8:9], v[8:9], 0, s[10:11]
	s_lshl_b32 s7, s6, 5
	s_lshl_b32 s9, s8, 5
	s_add_i32 s14, s4, 0x1ea00
	s_lshl_b32 s15, s8, 1
	s_movk_i32 s16, 0x5800
	v_add_u32_e32 v17, 0x400, v16
	v_add_u32_e32 v18, 0x800, v16
	v_add_u32_e32 v19, 0xc00, v16
	v_add_u32_e32 v20, 0x1000, v16
	v_add_u32_e32 v21, 0x1400, v16
	v_add_u32_e32 v22, 0x1800, v16
	v_add_u32_e32 v23, 0x1c00, v16
	s_branch .Lxp0_611

.Lxp0_613:
	s_andn2_b64 vcc, exec, s[10:11]
	s_cbranch_vccnz .Lxp0_610
	s_mul_hi_i32 s4, s6, 0x2e8ba2e9
	s_lshr_b32 s10, s4, 31
	s_ashr_i32 s4, s4, 5
	s_add_i32 s10, s4, s10
	s_mul_i32 s11, s10, 0xffffea00
	s_mul_i32 s4, s10, 0xffffff50
	s_add_i32 s18, s7, s11
	s_add_i32 s4, s6, s4
	s_add_i32 s11, s18, 0xfffff500
	s_cmpk_lt_i32 s4, 0x58
	s_cselect_b32 s11, s18, s11
	s_cselect_b32 s4, 0, 0x80
	s_lshl_b32 s10, s10, 6
	s_ashr_i32 s19, s18, 31
	v_or_b32_e32 v0, s10, v10
	v_lshl_add_u64 v[24:25], s[18:19], 2, v[6:7]
	v_mad_i64_i32 v[26:27], s[18:19], v0, s16, v[24:25]
	v_or_b32_e32 v28, 2, v0
	v_or_b32_e32 v30, 4, v0
	v_or_b32_e32 v32, 6, v0
	v_or_b32_e32 v34, 8, v0
	v_or_b32_e32 v36, 10, v0
	v_or_b32_e32 v38, 12, v0
	v_or_b32_e32 v40, 14, v0
	v_mad_i64_i32 v[28:29], s[18:19], v28, s16, v[24:25]
	v_mad_i64_i32 v[30:31], s[18:19], v30, s16, v[24:25]
	v_mad_i64_i32 v[32:33], s[18:19], v32, s16, v[24:25]
	v_mad_i64_i32 v[34:35], s[18:19], v34, s16, v[24:25]
	v_mad_i64_i32 v[36:37], s[18:19], v36, s16, v[24:25]
	v_mad_i64_i32 v[38:39], s[18:19], v38, s16, v[24:25]
	v_mad_i64_i32 v[40:41], s[18:19], v40, s16, v[24:25]
	global_load_dword v42, v[26:27], off
	global_load_dword v43, v[28:29], off
	global_load_dword v44, v[30:31], off
	global_load_dword v45, v[32:33], off
	global_load_dword v46, v[34:35], off
	global_load_dword v47, v[36:37], off
	global_load_dword v48, v[38:39], off
	global_load_dword v49, v[40:41], off
	v_or_b32_e32 v26, 16, v0
	v_mad_i64_i32 v[26:27], s[18:19], v26, s16, v[24:25]
	v_or_b32_e32 v28, 18, v0
	v_or_b32_e32 v30, 20, v0
	v_or_b32_e32 v32, 22, v0
	v_or_b32_e32 v34, 24, v0
	v_or_b32_e32 v36, 26, v0
	v_or_b32_e32 v38, 28, v0
	v_or_b32_e32 v40, 30, v0
	v_mad_i64_i32 v[28:29], s[18:19], v28, s16, v[24:25]
	v_mad_i64_i32 v[30:31], s[18:19], v30, s16, v[24:25]
	v_mad_i64_i32 v[32:33], s[18:19], v32, s16, v[24:25]
	v_mad_i64_i32 v[34:35], s[18:19], v34, s16, v[24:25]
	v_mad_i64_i32 v[36:37], s[18:19], v36, s16, v[24:25]
	v_mad_i64_i32 v[38:39], s[18:19], v38, s16, v[24:25]
	v_mad_i64_i32 v[40:41], s[18:19], v40, s16, v[24:25]
	global_load_dword v50, v[26:27], off
	global_load_dword v51, v[28:29], off
	global_load_dword v52, v[30:31], off
	global_load_dword v53, v[32:33], off
	global_load_dword v54, v[34:35], off
	global_load_dword v55, v[36:37], off
	global_load_dword v56, v[38:39], off
	global_load_dword v57, v[40:41], off
	v_or_b32_e32 v26, 32, v0
	v_mad_i64_i32 v[26:27], s[18:19], v26, s16, v[24:25]
	v_or_b32_e32 v28, 34, v0
	v_or_b32_e32 v30, 36, v0
	v_or_b32_e32 v32, 38, v0
	v_or_b32_e32 v34, 40, v0
	v_or_b32_e32 v36, 42, v0
	v_or_b32_e32 v38, 44, v0
	v_or_b32_e32 v40, 46, v0
	v_mad_i64_i32 v[28:29], s[18:19], v28, s16, v[24:25]
	v_mad_i64_i32 v[30:31], s[18:19], v30, s16, v[24:25]
	v_mad_i64_i32 v[32:33], s[18:19], v32, s16, v[24:25]
	v_mad_i64_i32 v[34:35], s[18:19], v34, s16, v[24:25]
	v_mad_i64_i32 v[36:37], s[18:19], v36, s16, v[24:25]
	v_mad_i64_i32 v[38:39], s[18:19], v38, s16, v[24:25]
	v_mad_i64_i32 v[40:41], s[18:19], v40, s16, v[24:25]
	global_load_dword v58, v[26:27], off
	global_load_dword v59, v[28:29], off
	global_load_dword v60, v[30:31], off
	global_load_dword v61, v[32:33], off
	global_load_dword v62, v[34:35], off
	global_load_dword v63, v[36:37], off
	global_load_dword v64, v[38:39], off
	global_load_dword v65, v[40:41], off
	v_or_b32_e32 v26, 48, v0
	v_mad_i64_i32 v[26:27], s[18:19], v26, s16, v[24:25]
	v_or_b32_e32 v28, 50, v0
	v_or_b32_e32 v30, 52, v0
	v_or_b32_e32 v32, 54, v0
	v_or_b32_e32 v34, 56, v0
	v_or_b32_e32 v36, 58, v0
	v_or_b32_e32 v38, 60, v0
	v_or_b32_e32 v0, 62, v0
	v_mad_i64_i32 v[28:29], s[18:19], v28, s16, v[24:25]
	v_mad_i64_i32 v[30:31], s[18:19], v30, s16, v[24:25]
	v_mad_i64_i32 v[32:33], s[18:19], v32, s16, v[24:25]
	v_mad_i64_i32 v[34:35], s[18:19], v34, s16, v[24:25]
	v_mad_i64_i32 v[36:37], s[18:19], v36, s16, v[24:25]
	v_mad_i64_i32 v[38:39], s[18:19], v38, s16, v[24:25]
	v_mad_i64_i32 v[24:25], s[18:19], v0, s16, v[24:25]
	global_load_dword v0, v[26:27], off
	global_load_dword v40, v[28:29], off
	global_load_dword v41, v[30:31], off
	global_load_dword v66, v[32:33], off
	global_load_dword v67, v[34:35], off
	global_load_dword v68, v[36:37], off
	global_load_dword v69, v[38:39], off
	global_load_dword v70, v[24:25], off
	s_waitcnt vmcnt(30)
	ds_write2_b32 v16, v42, v43 offset1:66
	s_waitcnt vmcnt(28)
	ds_write2_b32 v16, v44, v45 offset0:132 offset1:198
	s_waitcnt vmcnt(26)
	ds_write2_b32 v17, v46, v47 offset0:8 offset1:74
	s_waitcnt vmcnt(24)
	ds_write2_b32 v17, v48, v49 offset0:140 offset1:206
	s_waitcnt vmcnt(22)
	ds_write2_b32 v18, v50, v51 offset0:16 offset1:82
	s_waitcnt vmcnt(20)
	ds_write2_b32 v18, v52, v53 offset0:148 offset1:214
	s_waitcnt vmcnt(18)
	ds_write2_b32 v19, v54, v55 offset0:24 offset1:90
	s_waitcnt vmcnt(16)
	ds_write2_b32 v19, v56, v57 offset0:156 offset1:222
	s_waitcnt vmcnt(14)
	ds_write2_b32 v20, v58, v59 offset0:32 offset1:98
	s_waitcnt vmcnt(12)
	ds_write2_b32 v20, v60, v61 offset0:164 offset1:230
	s_waitcnt vmcnt(10)
	ds_write2_b32 v21, v62, v63 offset0:40 offset1:106
	s_waitcnt vmcnt(8)
	ds_write2_b32 v21, v64, v65 offset0:172 offset1:238
	s_waitcnt vmcnt(6)
	ds_write2_b32 v22, v0, v40 offset0:48 offset1:114
	s_waitcnt vmcnt(4)
	ds_write2_b32 v22, v41, v66 offset0:180 offset1:246
	s_waitcnt vmcnt(2)
	ds_write2_b32 v23, v67, v68 offset0:56 offset1:122
	s_waitcnt vmcnt(0)
	ds_write2_b32 v23, v69, v70 offset0:188 offset1:254
	s_waitcnt lgkmcnt(0)
	ds_read2_b32 v[24:25], v12 offset1:33
	s_waitcnt lgkmcnt(0)
	v_cvt_pk_bf16_f32 v24, v24, v25
	ds_read2_b32 v[26:27], v12 offset0:66 offset1:99
	s_lshl_b32 s17, s11, 1
	s_and_b32 s11, s11, 0x60
	s_waitcnt lgkmcnt(0)
	v_cvt_pk_bf16_f32 v25, v26, v27
	ds_read2_b32 v[26:27], v12 offset0:132 offset1:165
	s_and_b32 s17, s17, 0xffffff00
	s_or_b32 s4, s11, s4
	s_waitcnt lgkmcnt(0)
	v_cvt_pk_bf16_f32 v26, v26, v27
	ds_read2_b32 v[28:29], v12 offset0:198 offset1:231
	s_or_b32 s4, s4, s17
	s_waitcnt lgkmcnt(0)
	v_cvt_pk_bf16_f32 v27, v28, v29
	v_or_b32_e32 v28, s4, v11
	s_ashr_i32 s11, s10, 31
	v_ashrrev_i32_e32 v29, 31, v28
	v_lshl_add_u64 v[30:31], s[10:11], 1, v[8:9]
	v_lshlrev_b64 v[28:29], 11, v[28:29]
	v_lshl_add_u64 v[28:29], v[30:31], 0, v[28:29]
	ds_read2_b32 v[32:33], v12 offset0:8 offset1:41
	global_store_dwordx4 v[28:29], v[24:27], off
	s_waitcnt lgkmcnt(0)
	s_nop 0
	v_cvt_pk_bf16_f32 v24, v32, v33
	ds_read2_b32 v[26:27], v12 offset0:74 offset1:107
	s_waitcnt lgkmcnt(0)
	v_cvt_pk_bf16_f32 v25, v26, v27
	ds_read2_b32 v[26:27], v12 offset0:140 offset1:173
	s_waitcnt lgkmcnt(0)
	v_cvt_pk_bf16_f32 v26, v26, v27
	ds_read2_b32 v[28:29], v12 offset0:206 offset1:239
	s_waitcnt lgkmcnt(0)
	v_cvt_pk_bf16_f32 v27, v28, v29
	v_or_b32_e32 v28, s4, v13
	v_ashrrev_i32_e32 v29, 31, v28
	v_lshlrev_b64 v[28:29], 11, v[28:29]
	v_lshl_add_u64 v[28:29], v[30:31], 0, v[28:29]
	ds_read2_b32 v[32:33], v12 offset0:16 offset1:49
	global_store_dwordx4 v[28:29], v[24:27], off
	s_waitcnt lgkmcnt(0)
	s_nop 0
	v_cvt_pk_bf16_f32 v24, v32, v33
	ds_read2_b32 v[26:27], v12 offset0:82 offset1:115
	s_waitcnt lgkmcnt(0)
	v_cvt_pk_bf16_f32 v25, v26, v27
	ds_read2_b32 v[26:27], v12 offset0:148 offset1:181
	s_waitcnt lgkmcnt(0)
	v_cvt_pk_bf16_f32 v26, v26, v27
	ds_read2_b32 v[28:29], v12 offset0:214 offset1:247
	s_waitcnt lgkmcnt(0)
	v_cvt_pk_bf16_f32 v27, v28, v29
	v_or_b32_e32 v28, s4, v14
	v_ashrrev_i32_e32 v29, 31, v28
	v_lshlrev_b64 v[28:29], 11, v[28:29]
	v_lshl_add_u64 v[28:29], v[30:31], 0, v[28:29]
	ds_read2_b32 v[32:33], v12 offset0:24 offset1:57
	global_store_dwordx4 v[28:29], v[24:27], off
	s_waitcnt lgkmcnt(0)
	s_nop 0
	v_cvt_pk_bf16_f32 v24, v32, v33
	ds_read2_b32 v[26:27], v12 offset0:90 offset1:123
	s_waitcnt lgkmcnt(0)
	v_cvt_pk_bf16_f32 v25, v26, v27
	ds_read2_b32 v[26:27], v12 offset0:156 offset1:189
	s_waitcnt lgkmcnt(0)
	v_cvt_pk_bf16_f32 v26, v26, v27
	ds_read2_b32 v[28:29], v12 offset0:222 offset1:255
	s_waitcnt lgkmcnt(0)
	v_cvt_pk_bf16_f32 v27, v28, v29
	v_or_b32_e32 v28, s4, v15
	v_ashrrev_i32_e32 v29, 31, v28
	v_lshlrev_b64 v[28:29], 11, v[28:29]
	v_lshl_add_u64 v[28:29], v[30:31], 0, v[28:29]
	global_store_dwordx4 v[28:29], v[24:27], off
	s_waitcnt lgkmcnt(0)
	s_branch .Lxp0_610
.Lxp0_end:
	s_waitcnt vmcnt(0)
	s_barrier
	s_and_saveexec_b64 s[42:43], s[12:13]
	s_cbranch_execz .LBB0_605
	s_add_i32 s4, 0, 0x20020
	v_mov_b32_e32 v0, s4
	s_waitcnt vmcnt(0) expcnt(0) lgkmcnt(0)
	ds_read_b32 v0, v0
	s_add_i32 s4, 0, 0x20024
	v_mov_b32_e32 v1, s4
	ds_read_b32 v2, v1
	s_waitcnt lgkmcnt(1)
	v_cmp_ne_u32_e32 vcc, 0, v0
	s_cbranch_vccnz .LBB0_576
	s_mov_b64 s[4:5], 0x4200
	v_lshl_add_u64 v[0:1], v[128:129], 0, s[4:5]
	s_mov_b64 s[4:5], 0x4400
	s_waitcnt lgkmcnt(0)
	v_lshl_add_u64 v[2:3], v[128:129], 0, s[4:5]
	s_mov_b64 s[4:5], 0x4500
	s_load_dword s6, s[80:81], 0x14
	v_lshl_add_u64 v[4:5], v[128:129], 0, s[4:5]
	s_mov_b64 s[4:5], 0x4600
	v_lshl_add_u64 v[6:7], v[128:129], 0, s[4:5]
	s_mov_b64 s[4:5], 0x4700
	v_lshl_add_u64 v[8:9], v[128:129], 0, s[4:5]
	s_mov_b64 s[4:5], 0x4800
	v_lshl_add_u64 v[10:11], v[128:129], 0, s[4:5]
	s_mov_b64 s[4:5], 0x4900
	v_lshl_add_u64 v[12:13], v[128:129], 0, s[4:5]
	s_mov_b64 s[4:5], 0x4a00
	s_waitcnt lgkmcnt(0)
	s_lshr_b32 s8, s6, 16
	s_and_b32 s6, s6, 0xffff
	v_lshl_add_u64 v[14:15], v[128:129], 0, s[4:5]
	s_mov_b64 s[4:5], 0x4b00
	s_cmp_lg_u32 s6, 0
	v_lshl_add_u64 v[16:17], v[128:129], 0, s[4:5]
	s_mov_b64 s[4:5], 0x4c00
	s_cselect_b64 s[6:7], -1, 0
	v_lshl_add_u64 v[18:19], v[128:129], 0, s[4:5]
	s_mov_b64 s[4:5], 0x4d00
	s_cmp_lg_u64 s[6:7], 0
	v_lshl_add_u64 v[20:21], v[128:129], 0, s[4:5]
	s_mov_b64 s[4:5], 0x4e00
	s_addc_u32 s6, s39, 0
	v_lshl_add_u64 v[22:23], v[128:129], 0, s[4:5]
	s_mov_b64 s[4:5], 0x4f00
	s_cmp_lg_u32 s8, 0
	v_lshl_add_u64 v[24:25], v[128:129], 0, s[4:5]
	s_mov_b64 s[4:5], 0x5000
	s_mul_i32 s24, s6, s38
	s_cselect_b64 s[6:7], -1, 0
	v_lshl_add_u64 v[26:27], v[128:129], 0, s[4:5]
	s_mov_b64 s[4:5], 0x5100
	s_cmp_lg_u64 s[6:7], 0
	v_lshl_add_u64 v[28:29], v[128:129], 0, s[4:5]
	s_mov_b64 s[4:5], 0x5200
	s_addc_u32 s6, s78, 0
	v_lshl_add_u64 v[30:31], v[128:129], 0, s[4:5]
	s_mov_b64 s[4:5], 0x5300
	s_mul_i32 s24, s24, s6
	v_lshl_add_u64 v[32:33], v[128:129], 0, s[4:5]
	s_mov_b32 s25, 1
	s_mov_b64 s[4:5], 0
	s_branch .LBB0_566

.LBB0_608:
	s_cmpk_gt_i32 s6, 0x107f
	s_branch .LBB0_615

.LBB0_789:
	s_or_b64 exec, exec, s[42:43]
	v_mov_b32_e32 v0, v152
	s_mov_b32 s34, s38
	s_mov_b32 s35, s2
	v_mov_b32_e32 v8, v152
	s_waitcnt lgkmcnt(0)
	s_barrier
	s_mov_b32 s4, 0
	s_cmpk_gt_i32 s35, 0x57f
	v_readfirstlane_b32 s5, v8
	s_cbranch_scc1 .LBB0_805
	v_lshlrev_b32_e32 v0, 4, v8
	v_add_u32_e32 v1, 0x2000, v0
	v_ashrrev_i32_e32 v2, 31, v1
	v_lshrrev_b32_e32 v2, 22, v2
	v_add_u32_e32 v2, v1, v2
	s_waitcnt vmcnt(7)
	v_ashrrev_i32_e32 v9, 10, v2
	v_mul_i32_i24_e32 v2, 0x400, v9
	v_sub_u32_e32 v1, v1, v2
	v_lshrrev_b32_e32 v2, 4, v1
	v_bitop3_b32 v1, v2, v1, 32 bitop3:0x6c
	s_load_dwordx2 s[6:7], s[0:1], 0xe0
	v_ashrrev_i32_e32 v2, 31, v1
	v_lshrrev_b32_e32 v2, 26, v2
	v_add_u32_e32 v2, v1, v2
	v_lshlrev_b32_e32 v3, 3, v9
	s_waitcnt vmcnt(6)
	v_ashrrev_i32_e32 v10, 6, v2
	v_and_b32_e32 v3, -16, v3
	s_ashr_i32 s9, s4, 31
	v_add_u32_e32 v3, v10, v3
	s_waitcnt lgkmcnt(0)
	s_add_u32 s8, s6, s4
	v_and_b32_e32 v4, 3, v10
	s_mov_b32 s4, 0x1fffe0
	v_lshrrev_b32_e32 v5, 2, v3
	v_lshlrev_b32_e32 v6, 1, v3
	v_and_b32_e32 v2, 0xc0, v2
	v_and_or_b32 v4, v3, s4, v4
	v_and_b32_e32 v5, 4, v5
	v_and_b32_e32 v6, 24, v6
	v_sub_u32_e32 v1, v1, v2
	v_mov_b32_e32 v2, 1
	v_or3_b32 v4, v4, v5, v6
	v_lshlrev_b32_e32 v5, 5, v9
	v_ashrrev_i16_sdwa v1, v2, sext(v1) dst_sel:DWORD dst_unused:UNUSED_PAD src0_sel:DWORD src1_sel:BYTE_0
	v_and_b32_e32 v5, 32, v5
	s_waitcnt vmcnt(5)
	v_bfe_i32 v11, v1, 0, 16
	v_add_lshl_u32 v1, v5, v11, 1
	v_lshl_add_u32 v132, v4, 11, v1
	v_lshl_add_u32 v134, v3, 11, v1
	v_bfe_i32 v1, v8, 27, 1
	v_lshrrev_b32_e32 v1, 22, v1
	v_add_u32_e32 v1, v0, v1
	v_and_b32_e32 v1, 0xfffffc00, v1
	v_sub_u32_e32 v0, v0, v1
	v_lshrrev_b32_e32 v1, 4, v0
	v_bitop3_b32 v1, v1, v0, 32 bitop3:0x6c
	v_ashrrev_i32_e32 v0, 31, v0
	v_lshrrev_b32_e32 v0, 26, v0
	v_add_u32_e32 v0, v1, v0
	s_waitcnt vmcnt(4)
	v_ashrrev_i32_e32 v12, 6, v0
	v_ashrrev_i32_e32 v0, 31, v8
	v_lshrrev_b32_e32 v0, 26, v0
	s_addc_u32 s9, s7, s9
	v_add_u32_e32 v0, v8, v0
	s_add_u32 s36, s8, 0x2d00000
	s_waitcnt vmcnt(3)
	v_ashrrev_i32_e32 v13, 6, v0
	s_addc_u32 s37, s9, 0
	v_lshlrev_b32_e32 v0, 3, v13
	s_add_u32 s42, s8, 0xa500000
	v_and_b32_e32 v0, -16, v0
	s_addc_u32 s43, s9, 0
	v_add_u32_e32 v0, v12, v0
	v_and_b32_e32 v3, 3, v12
	s_ashr_i32 s45, s35, 31
	v_and_or_b32 v3, v0, s4, v3
	s_lshr_b32 s4, s45, 29
	s_add_i32 s4, s35, s4
	s_ashr_i32 s10, s5, 6
	s_ashr_i32 s6, s4, 3
	s_and_b32 s4, s4, -8
	s_ashr_i32 s14, s5, 8
	s_lshl_b32 s44, s10, 10
	s_sub_i32 s4, s35, s4
	s_cmp_lt_i32 s4, 0
	s_movk_i32 s46, 0xb1
	s_cselect_b32 s7, s46, 0xb0
	s_mul_i32 s4, s7, s4
	s_add_i32 s4, s4, s6
	s_mul_hi_i32 s6, s4, 0x2e8ba2e9
	s_lshr_b32 s7, s6, 31
	s_ashr_i32 s6, s6, 5
	s_add_i32 s6, s6, s7
	s_lshl_b32 s7, s6, 3
	s_mulk_i32 s6, 0xb0
	s_sub_i32 s6, s4, s6
	s_bfe_u32 s4, s6, 0x3001c
	s_add_i32 s11, s6, s4
	s_sext_i32_i16 s4, s11
	s_and_b32 s11, s11, 0xfff8
	v_lshrrev_b32_e32 v4, 2, v0
	v_lshlrev_b32_e32 v5, 1, v0
	s_sub_i32 s6, s6, s11
	v_and_b32_e32 v4, 4, v4
	v_and_b32_e32 v5, 24, v5
	s_sext_i32_i16 s6, s6
	v_or3_b32 v3, v3, v4, v5
	v_mul_i32_i24_e32 v5, 64, v12
	s_lshr_b32 s4, s4, 3
	s_add_i32 s24, s7, s6
	v_sub_u32_e32 v1, v1, v5
	s_ashr_i32 s25, s24, 31
	s_bfe_i64 s[16:17], s[4:5], 0x100000
	v_lshlrev_b32_e32 v4, 5, v13
	v_ashrrev_i16_sdwa v1, v2, sext(v1) dst_sel:DWORD dst_unused:UNUSED_PAD src0_sel:DWORD src1_sel:BYTE_0
	s_lshl_b64 s[6:7], s[24:25], 19
	s_lshl_b64 s[16:17], s[16:17], 19
	v_and_b32_e32 v4, 32, v4
	s_waitcnt vmcnt(2)
	v_bfe_i32 v14, v1, 0, 16
	s_add_u32 s28, s42, s16
	v_add_lshl_u32 v1, v4, v14, 1
	s_addc_u32 s29, s43, s17
	s_add_i32 s25, s44, 0
	v_lshl_add_u32 v136, v3, 11, v1
	s_add_i32 m0, s25, 0x10000
	v_lshl_add_u32 v138, v0, 11, v1
	global_load_lds_dwordx4 v136, s[28:29]
	s_add_i32 m0, s25, 0x12000
	s_add_u32 s16, s28, 0x40000
	global_load_lds_dwordx4 v132, s[28:29]
	s_addc_u32 s17, s29, 0
	s_add_i32 m0, s25, 0x14000
	v_mov_b32_e32 v137, 0
	global_load_lds_dwordx4 v136, s[16:17]
	s_add_i32 m0, s25, 0x16000
	s_add_u32 s26, s36, s6
	s_addc_u32 s27, s37, s7
	s_add_i32 s47, s25, 0x2000
	global_load_lds_dwordx4 v132, s[16:17]
	s_mov_b32 m0, s25
	s_add_u32 s6, s26, 0x40000
	global_load_lds_dwordx4 v138, s[26:27]
	s_mov_b32 m0, s47
	s_addc_u32 s7, s27, 0
	s_add_i32 s48, s25, 0x4000
	global_load_lds_dwordx4 v134, s[26:27]
	s_mov_b32 m0, s48
	s_add_i32 s49, s25, 0x6000
	global_load_lds_dwordx4 v138, s[6:7]
	s_mov_b32 m0, s49
	v_mov_b32_e32 v133, v137
	global_load_lds_dwordx4 v134, s[6:7]
	v_mov_b32_e32 v139, v137
	v_mov_b32_e32 v135, v137
	s_cmp_eq_u32 s14, 1
	s_mov_b32 s50, 0
	v_lshl_add_u64 v[6:7], s[28:29], 0, v[136:137]
	v_lshl_add_u64 v[4:5], s[28:29], 0, v[132:133]
	v_lshl_add_u64 v[0:1], s[26:27], 0, v[138:139]
	s_cselect_b64 s[6:7], -1, 0
	s_cmp_lg_u32 s14, 1
	v_lshl_add_u64 v[2:3], s[26:27], 0, v[134:135]
	s_cbranch_scc1 .LBB0_792
	s_barrier

.LBB0_854:
	v_ashrrev_i32_e32 v1, 31, v8
	v_lshrrev_b32_e32 v1, 26, v1
	v_add_u32_e32 v1, v8, v1
	v_ashrrev_i32_e32 v9, 6, v1
	v_bfe_i32 v1, v8, 27, 1
	v_lshlrev_b32_e32 v0, 4, v8
	v_lshrrev_b32_e32 v1, 22, v1
	v_add_u32_e32 v1, v0, v1
	v_and_b32_e32 v1, 0xfffffc00, v1
	v_sub_u32_e32 v1, v0, v1
	v_lshrrev_b32_e32 v2, 4, v1
	v_bitop3_b32 v2, v2, v1, 32 bitop3:0x6c
	v_ashrrev_i32_e32 v1, 31, v1
	s_ashr_i32 s5, s4, 31
	v_lshrrev_b32_e32 v1, 26, v1
	s_waitcnt lgkmcnt(0)
	s_add_u32 s8, s8, s4
	v_lshlrev_b32_e32 v3, 3, v9
	v_add_u32_e32 v1, v2, v1
	s_addc_u32 s9, s9, s5
	v_and_b32_e32 v3, 0xfffff0, v3
	v_ashrrev_i32_e32 v11, 6, v1
	s_add_u32 s45, s8, 0x4d00000
	v_add_u32_e32 v1, v11, v3
	v_lshlrev_b32_e32 v3, 5, v9
	s_addc_u32 s46, s9, 0
	v_and_b32_e32 v10, 32, v3
	v_mul_i32_i24_e32 v3, 64, v11
	s_add_u32 s47, s8, 0xb000000
	v_sub_u32_e32 v2, v2, v3
	v_mov_b32_e32 v3, 1
	s_movk_i32 s20, 0xb00
	s_addc_u32 s48, s9, 0
	v_ashrrev_i16_sdwa v2, v3, sext(v2) dst_sel:DWORD dst_unused:UNUSED_PAD src0_sel:DWORD src1_sel:BYTE_0
	v_mul_lo_u32 v1, v1, s20
	s_add_i32 s8, s14, s10
	v_bfe_i32 v12, v2, 0, 16
	v_or_b32_e32 v1, v1, v10
	v_add_u32_e32 v0, 0x2000, v0
	s_ashr_i32 s9, s8, 31
	v_add_lshl_u32 v132, v1, v12, 1
	v_ashrrev_i32_e32 v1, 31, v0
	s_lshr_b32 s9, s9, 27
	v_lshrrev_b32_e32 v1, 22, v1
	s_add_i32 s9, s8, s9
	v_add_u32_e32 v1, v0, v1
	s_ashr_i32 s10, s9, 5
	s_and_b32 s9, s9, 0xffe0
	v_ashrrev_i32_e32 v13, 10, v1
	s_sub_i32 s8, s8, s9
	v_mul_i32_i24_e32 v1, 0x400, v13
	s_bfe_i32 s9, s8, 0x80000
	v_sub_u32_e32 v0, v0, v1
	s_bfe_u32 s9, s9, 0x3000c
	v_lshrrev_b32_e32 v1, 4, v0
	s_add_i32 s9, s8, s9
	v_bitop3_b32 v0, v1, v0, 32 bitop3:0x6c
	s_bfe_i32 s11, s9, 0x80000
	s_and_b32 s9, s9, 0xf8
	v_ashrrev_i32_e32 v2, 31, v0
	s_sub_i32 s8, s8, s9
	v_lshrrev_b32_e32 v2, 26, v2
	s_lshl_b32 s10, s10, 3
	s_sext_i32_i16 s11, s11
	s_sext_i32_i8 s8, s8
	v_add_u32_e32 v2, v0, v2
	s_ashr_i32 s16, s18, 6
	s_add_i32 s66, s10, s8
	s_ashr_i32 s8, s11, 3
	s_ashr_i32 s19, s18, 8
	v_lshlrev_b32_e32 v1, 3, v13
	v_ashrrev_i32_e32 v14, 6, v2
	v_and_b32_e32 v2, 0xc0, v2
	s_lshl_b32 s49, s16, 10
	s_lshr_b32 s21, s11, 3
	s_mul_hi_i32 s9, s8, 0x160000
	s_mul_i32 s8, s8, 0x160000
	v_and_b32_e32 v1, 0xfffff0, v1
	v_sub_u32_e32 v0, v0, v2
	s_add_u32 s30, s47, s8
	v_add_u32_e32 v1, v14, v1
	v_lshlrev_b32_e32 v4, 5, v13
	v_ashrrev_i16_sdwa v0, v3, sext(v0) dst_sel:DWORD dst_unused:UNUSED_PAD src0_sel:DWORD src1_sel:BYTE_0
	s_addc_u32 s31, s48, s9
	s_add_i32 s50, s49, 0
	v_and_b32_e32 v15, 32, v4
	v_bfe_i32 v16, v0, 0, 16
	v_mul_lo_u32 v0, v1, s20
	s_add_i32 m0, s50, 0x10000
	v_or_b32_e32 v0, v0, v15
	global_load_lds_dwordx4 v132, s[30:31]
	s_add_i32 m0, s50, 0x12000
	v_add_lshl_u32 v134, v0, v16, 1
	s_add_u32 s8, s30, 0xb0000
	global_load_lds_dwordx4 v134, s[30:31]
	s_addc_u32 s9, s31, 0
	s_add_i32 m0, s50, 0x14000
	s_mul_i32 s14, s66, 0x160000
	global_load_lds_dwordx4 v132, s[8:9]
	s_add_i32 m0, s50, 0x16000
	s_mul_hi_i32 s10, s66, 0x160000
	s_add_u32 s28, s45, s14
	s_addc_u32 s29, s46, s10
	s_add_i32 s51, s50, 0x2000
	global_load_lds_dwordx4 v134, s[8:9]
	s_mov_b32 m0, s50
	s_add_u32 s8, s28, 0xb0000
	global_load_lds_dwordx4 v132, s[28:29]
	s_mov_b32 m0, s51
	s_addc_u32 s9, s29, 0
	s_add_i32 s52, s50, 0x4000
	global_load_lds_dwordx4 v134, s[28:29]
	s_mov_b32 m0, s52
	s_add_i32 s53, s50, 0x6000
	global_load_lds_dwordx4 v132, s[8:9]
	s_mov_b32 m0, s53
	v_mov_b32_e32 v133, 0
	global_load_lds_dwordx4 v134, s[8:9]
	v_mov_b32_e32 v135, v133
	s_cmp_eq_u32 s19, 1
	s_mov_b32 s54, 0
	v_lshl_add_u64 v[6:7], s[30:31], 0, v[132:133]
	v_lshl_add_u64 v[4:5], s[30:31], 0, v[134:135]
	s_mov_b64 s[8:9], 0xb0000
	v_lshl_add_u64 v[0:1], s[28:29], 0, v[132:133]
	s_cselect_b64 s[10:11], -1, 0
	s_cmp_lg_u32 s19, 1
	v_lshl_add_u64 v[2:3], s[28:29], 0, v[134:135]
	s_cbranch_scc1 .LBB0_856
	s_barrier

.LBB0_1399:
	s_mov_b32 s99, 0
	s_add_u32 s34, s16, 0x6d00000
	s_addc_u32 s35, s17, 0
	s_add_u32 s36, s16, 0x800000
	s_addc_u32 s37, s17, 0
	s_add_u32 s56, s16, 0x5d00000
	s_addc_u32 s57, s17, 0
	s_add_u32 s42, s16, 0x8d00000
	s_addc_u32 s43, s17, 0
	s_add_u32 s44, s16, 0xa500000
	s_addc_u32 s45, s17, 0
	s_add_u32 s46, s16, 0xfd00000
	s_addc_u32 s47, s17, 0
	s_add_u32 s6, s30, s28
	s_addc_u32 s7, s31, s29
	s_add_u32 s28, s6, 0xfd01000
	s_addc_u32 s29, s7, 0
	s_add_u32 s30, s6, 0xa520000
	s_addc_u32 s31, s7, 0
	s_add_i32 s58, 0, 0x20000
	s_mov_b32 s15, 0
	v_cmp_eq_u32_e64 s[4:5], 0, v154
	v_mov_b32_e32 v101, 0
	v_mov_b32_e32 v110, s58
	s_movk_i32 s59, 0x2ff
	s_mov_b32 s60, 0xc2fc0000
	s_mov_b32 s61, 0x800000
	s_movk_i32 s62, 0x7f
	s_mov_b64 s[48:49], 0x1000
	s_movk_i32 s63, 0x1000
	s_movk_i32 s64, 0xff
	s_movk_i32 s65, 0x68
	s_movk_i32 s66, 0x600
	s_movk_i32 s67, 0x100
	s_movk_i32 s68, 0x48
	s_mov_b32 s69, 0xf149f2ca
	s_mov_b32 s70, 0x3e16c740
	s_mov_b64 s[50:51], 0x20000
	v_mov_b32_e32 v111, 0x42800000
	v_mov_b32_e32 v112, 0x42000000
	v_not_b32_e32 v113, 63
	v_mov_b32_e32 v114, 0x80
	v_mov_b32_e32 v115, 0xf149f2ca
	s_branch .LBB0_1403

.LBB0_1403:
	s_barrier
	s_and_saveexec_b64 s[6:7], s[4:5]
	s_cbranch_execz .LBB0_1407
	s_mov_b64 s[10:11], exec
	s_waitcnt vmcnt(16)
	v_mbcnt_lo_u32_b32 v0, s10, 0
	v_mbcnt_hi_u32_b32 v0, s11, v0
	v_cmp_eq_u32_e32 vcc, 0, v0
	s_and_saveexec_b64 s[8:9], vcc
	s_cbranch_execz .LBB0_1406
	s_bcnt1_i32_b64 s10, s[10:11]
	s_waitcnt vmcnt(15)
	v_mov_b32_e32 v1, s10
	s_cmp_eq_u32 s99, 0
	s_cbranch_scc1 .Lxp1_noinc
	global_atomic_add v101, v1, s[16:17] offset:1024
.Lxp1_noinc:
	global_atomic_add v1, v101, v1, s[16:17] offset:512 sc0

.Lxp1_wloop:
	global_load_dword v0, v101, s[16:17] offset:1024 sc1
	s_waitcnt vmcnt(0)
	v_cmp_gt_u32_e32 vcc, 0x300, v0
	s_cbranch_vccz .Lxp1_wdone
	s_sub_u32 s98, s98, 1
	s_cmp_eq_u32 s98, 0
	s_cbranch_scc1 .Lxp1_wdone
	s_sleep 8
	s_branch .Lxp1_wloop
.Lxp1_wdone:
	s_or_b64 exec, exec, s[6:7]
	s_barrier
	s_mov_b32 s10, 0
	s_mov_b32 s11, 0
	s_load_dwordx2 s[14:15], s[0:1], 0xe0
	v_mov_b32_e32 v23, v152
	v_and_b32_e32 v22, 63, v23
	v_lshlrev_b32_e32 v8, 3, v22
	v_readfirstlane_b32 s4, v23
	s_ashr_i32 s26, s4, 6
	s_sub_u32 s5, s2, 64
	s_lshl_b32 s5, s5, 3
	s_add_i32 s6, s5, s26
	s_sub_u32 s4, s38, 64
	s_lshl_b32 s8, s4, 3
	s_mov_b32 s16, s0
	s_mov_b32 s17, s1
	s_waitcnt lgkmcnt(0)
	s_cmpk_gt_i32 s6, 0x107f
	s_cbranch_scc1 .Lxp1_end
	s_load_dwordx4 s[20:23], s[16:17], 0xc0
	s_waitcnt lgkmcnt(0)
	s_add_u32 s10, s14, s10
	v_mov_b32_e32 v1, 0
	v_and_b32_e32 v4, 56, v8
	s_addc_u32 s11, s15, s11
	s_lshl_b32 s4, s26, 14
	v_lshlrev_b32_e32 v0, 2, v23
	s_waitcnt vmcnt(5)
	v_lshrrev_b32_e32 v11, 3, v22
	v_mul_u32_u24_e32 v6, 0x84, v4
	v_lshlrev_b32_e32 v4, 1, v4
	v_mov_b32_e32 v5, v1
	s_add_i32 s4, s4, 0
	v_lshrrev_b32_e32 v10, 5, v22
	v_and_b32_e32 v0, 0x7c, v0
	v_lshl_add_u64 v[8:9], s[10:11], 0, v[4:5]
	s_mov_b64 s[10:11], 0xb000000
	v_lshlrev_b32_e32 v7, 2, v11
	s_waitcnt vmcnt(0)
	v_add_u32_e32 v16, s4, v0
	v_mul_u32_u24_e32 v17, 0x84, v10
	v_lshl_add_u64 v[4:5], v[8:9], 0, s[10:11]
	v_add3_u32 v12, s4, v6, v7
	v_lshl_add_u64 v[6:7], s[20:21], 0, v[0:1]
	s_mov_b64 s[10:11], 0x1600000
	v_lshl_add_u64 v[2:3], s[22:23], 0, v[0:1]
	s_mov_b64 s[14:15], 0xb00000
	v_lshl_add_u64 v[6:7], v[6:7], 0, s[10:11]
	s_mov_b64 s[10:11], 0xa500000
	s_lshl_b32 s4, s6, 1
	v_add_u32_e32 v16, v16, v17
	s_mov_b32 s5, 0
	v_lshl_add_u64 v[2:3], v[2:3], 0, s[14:15]
	v_or_b32_e32 v13, 8, v11
	v_or_b32_e32 v14, 16, v11
	v_or_b32_e32 v15, 24, v11
	v_lshl_add_u64 v[8:9], v[8:9], 0, s[10:11]
	s_lshl_b32 s7, s6, 5
	s_lshl_b32 s9, s8, 5
	s_add_i32 s14, s4, 0x1ea00
	s_lshl_b32 s15, s8, 1
	s_movk_i32 s16, 0x5800
	v_add_u32_e32 v17, 0x400, v16
	v_add_u32_e32 v18, 0x800, v16
	v_add_u32_e32 v19, 0xc00, v16
	v_add_u32_e32 v20, 0x1000, v16
	v_add_u32_e32 v21, 0x1400, v16
	v_add_u32_e32 v22, 0x1800, v16
	v_add_u32_e32 v23, 0x1c00, v16
	s_branch .Lxp1_1493

.Lxp1_1495:
	s_andn2_b64 vcc, exec, s[10:11]
	s_cbranch_vccnz .Lxp1_1492
	s_mul_hi_i32 s4, s6, 0x2e8ba2e9
	s_lshr_b32 s10, s4, 31
	s_ashr_i32 s4, s4, 5
	s_add_i32 s10, s4, s10
	s_mul_i32 s11, s10, 0xffffea00
	s_mul_i32 s4, s10, 0xffffff50
	s_add_i32 s18, s7, s11
	s_add_i32 s4, s6, s4
	s_add_i32 s11, s18, 0xfffff500
	s_cmpk_lt_i32 s4, 0x58
	s_cselect_b32 s11, s18, s11
	s_cselect_b32 s4, 0, 0x80
	s_lshl_b32 s10, s10, 6
	s_ashr_i32 s19, s18, 31
	v_or_b32_e32 v0, s10, v10
	v_lshl_add_u64 v[24:25], s[18:19], 2, v[6:7]
	v_mad_i64_i32 v[26:27], s[18:19], v0, s16, v[24:25]
	v_or_b32_e32 v28, 2, v0
	v_or_b32_e32 v30, 4, v0
	v_or_b32_e32 v32, 6, v0
	v_or_b32_e32 v34, 8, v0
	v_or_b32_e32 v36, 10, v0
	v_or_b32_e32 v38, 12, v0
	v_or_b32_e32 v40, 14, v0
	v_mad_i64_i32 v[28:29], s[18:19], v28, s16, v[24:25]
	v_mad_i64_i32 v[30:31], s[18:19], v30, s16, v[24:25]
	v_mad_i64_i32 v[32:33], s[18:19], v32, s16, v[24:25]
	v_mad_i64_i32 v[34:35], s[18:19], v34, s16, v[24:25]
	v_mad_i64_i32 v[36:37], s[18:19], v36, s16, v[24:25]
	v_mad_i64_i32 v[38:39], s[18:19], v38, s16, v[24:25]
	v_mad_i64_i32 v[40:41], s[18:19], v40, s16, v[24:25]
	global_load_dword v42, v[26:27], off
	global_load_dword v43, v[28:29], off
	global_load_dword v44, v[30:31], off
	global_load_dword v45, v[32:33], off
	global_load_dword v46, v[34:35], off
	global_load_dword v47, v[36:37], off
	global_load_dword v48, v[38:39], off
	global_load_dword v49, v[40:41], off
	v_or_b32_e32 v26, 16, v0
	v_mad_i64_i32 v[26:27], s[18:19], v26, s16, v[24:25]
	v_or_b32_e32 v28, 18, v0
	v_or_b32_e32 v30, 20, v0
	v_or_b32_e32 v32, 22, v0
	v_or_b32_e32 v34, 24, v0
	v_or_b32_e32 v36, 26, v0
	v_or_b32_e32 v38, 28, v0
	v_or_b32_e32 v40, 30, v0
	v_mad_i64_i32 v[28:29], s[18:19], v28, s16, v[24:25]
	v_mad_i64_i32 v[30:31], s[18:19], v30, s16, v[24:25]
	v_mad_i64_i32 v[32:33], s[18:19], v32, s16, v[24:25]
	v_mad_i64_i32 v[34:35], s[18:19], v34, s16, v[24:25]
	v_mad_i64_i32 v[36:37], s[18:19], v36, s16, v[24:25]
	v_mad_i64_i32 v[38:39], s[18:19], v38, s16, v[24:25]
	v_mad_i64_i32 v[40:41], s[18:19], v40, s16, v[24:25]
	global_load_dword v50, v[26:27], off
	global_load_dword v51, v[28:29], off
	global_load_dword v52, v[30:31], off
	global_load_dword v53, v[32:33], off
	global_load_dword v54, v[34:35], off
	global_load_dword v55, v[36:37], off
	global_load_dword v56, v[38:39], off
	global_load_dword v57, v[40:41], off
	v_or_b32_e32 v26, 32, v0
	v_mad_i64_i32 v[26:27], s[18:19], v26, s16, v[24:25]
	v_or_b32_e32 v28, 34, v0
	v_or_b32_e32 v30, 36, v0
	v_or_b32_e32 v32, 38, v0
	v_or_b32_e32 v34, 40, v0
	v_or_b32_e32 v36, 42, v0
	v_or_b32_e32 v38, 44, v0
	v_or_b32_e32 v40, 46, v0
	v_mad_i64_i32 v[28:29], s[18:19], v28, s16, v[24:25]
	v_mad_i64_i32 v[30:31], s[18:19], v30, s16, v[24:25]
	v_mad_i64_i32 v[32:33], s[18:19], v32, s16, v[24:25]
	v_mad_i64_i32 v[34:35], s[18:19], v34, s16, v[24:25]
	v_mad_i64_i32 v[36:37], s[18:19], v36, s16, v[24:25]
	v_mad_i64_i32 v[38:39], s[18:19], v38, s16, v[24:25]
	v_mad_i64_i32 v[40:41], s[18:19], v40, s16, v[24:25]
	global_load_dword v58, v[26:27], off
	global_load_dword v59, v[28:29], off
	global_load_dword v60, v[30:31], off
	global_load_dword v61, v[32:33], off
	global_load_dword v62, v[34:35], off
	global_load_dword v63, v[36:37], off
	global_load_dword v64, v[38:39], off
	global_load_dword v65, v[40:41], off
	v_or_b32_e32 v26, 48, v0
	v_mad_i64_i32 v[26:27], s[18:19], v26, s16, v[24:25]
	v_or_b32_e32 v28, 50, v0
	v_or_b32_e32 v30, 52, v0
	v_or_b32_e32 v32, 54, v0
	v_or_b32_e32 v34, 56, v0
	v_or_b32_e32 v36, 58, v0
	v_or_b32_e32 v38, 60, v0
	v_or_b32_e32 v0, 62, v0
	v_mad_i64_i32 v[28:29], s[18:19], v28, s16, v[24:25]
	v_mad_i64_i32 v[30:31], s[18:19], v30, s16, v[24:25]
	v_mad_i64_i32 v[32:33], s[18:19], v32, s16, v[24:25]
	v_mad_i64_i32 v[34:35], s[18:19], v34, s16, v[24:25]
	v_mad_i64_i32 v[36:37], s[18:19], v36, s16, v[24:25]
	v_mad_i64_i32 v[38:39], s[18:19], v38, s16, v[24:25]
	v_mad_i64_i32 v[24:25], s[18:19], v0, s16, v[24:25]
	global_load_dword v0, v[26:27], off
	global_load_dword v40, v[28:29], off
	global_load_dword v41, v[30:31], off
	global_load_dword v66, v[32:33], off
	global_load_dword v67, v[34:35], off
	global_load_dword v68, v[36:37], off
	global_load_dword v69, v[38:39], off
	global_load_dword v70, v[24:25], off
	s_waitcnt vmcnt(30)
	ds_write2_b32 v16, v42, v43 offset1:66
	s_waitcnt vmcnt(28)
	ds_write2_b32 v16, v44, v45 offset0:132 offset1:198
	s_waitcnt vmcnt(26)
	ds_write2_b32 v17, v46, v47 offset0:8 offset1:74
	s_waitcnt vmcnt(24)
	ds_write2_b32 v17, v48, v49 offset0:140 offset1:206
	s_waitcnt vmcnt(22)
	ds_write2_b32 v18, v50, v51 offset0:16 offset1:82
	s_waitcnt vmcnt(20)
	ds_write2_b32 v18, v52, v53 offset0:148 offset1:214
	s_waitcnt vmcnt(18)
	ds_write2_b32 v19, v54, v55 offset0:24 offset1:90
	s_waitcnt vmcnt(16)
	ds_write2_b32 v19, v56, v57 offset0:156 offset1:222
	s_waitcnt vmcnt(14)
	ds_write2_b32 v20, v58, v59 offset0:32 offset1:98
	s_waitcnt vmcnt(12)
	ds_write2_b32 v20, v60, v61 offset0:164 offset1:230
	s_waitcnt vmcnt(10)
	ds_write2_b32 v21, v62, v63 offset0:40 offset1:106
	s_waitcnt vmcnt(8)
	ds_write2_b32 v21, v64, v65 offset0:172 offset1:238
	s_waitcnt vmcnt(6)
	ds_write2_b32 v22, v0, v40 offset0:48 offset1:114
	s_waitcnt vmcnt(4)
	ds_write2_b32 v22, v41, v66 offset0:180 offset1:246
	s_waitcnt vmcnt(2)
	ds_write2_b32 v23, v67, v68 offset0:56 offset1:122
	s_waitcnt vmcnt(0)
	ds_write2_b32 v23, v69, v70 offset0:188 offset1:254
	s_waitcnt lgkmcnt(0)
	ds_read2_b32 v[24:25], v12 offset1:33
	s_waitcnt lgkmcnt(0)
	v_cvt_pk_bf16_f32 v24, v24, v25
	ds_read2_b32 v[26:27], v12 offset0:66 offset1:99
	s_lshl_b32 s17, s11, 1
	s_and_b32 s11, s11, 0x60
	s_waitcnt lgkmcnt(0)
	v_cvt_pk_bf16_f32 v25, v26, v27
	ds_read2_b32 v[26:27], v12 offset0:132 offset1:165
	s_and_b32 s17, s17, 0xffffff00
	s_or_b32 s4, s11, s4
	s_waitcnt lgkmcnt(0)
	v_cvt_pk_bf16_f32 v26, v26, v27
	ds_read2_b32 v[28:29], v12 offset0:198 offset1:231
	s_or_b32 s4, s4, s17
	s_waitcnt lgkmcnt(0)
	v_cvt_pk_bf16_f32 v27, v28, v29
	v_or_b32_e32 v28, s4, v11
	s_ashr_i32 s11, s10, 31
	v_ashrrev_i32_e32 v29, 31, v28
	v_lshl_add_u64 v[30:31], s[10:11], 1, v[8:9]
	v_lshlrev_b64 v[28:29], 11, v[28:29]
	v_lshl_add_u64 v[28:29], v[30:31], 0, v[28:29]
	ds_read2_b32 v[32:33], v12 offset0:8 offset1:41
	global_store_dwordx4 v[28:29], v[24:27], off
	s_waitcnt lgkmcnt(0)
	s_nop 0
	v_cvt_pk_bf16_f32 v24, v32, v33
	ds_read2_b32 v[26:27], v12 offset0:74 offset1:107
	s_waitcnt lgkmcnt(0)
	v_cvt_pk_bf16_f32 v25, v26, v27
	ds_read2_b32 v[26:27], v12 offset0:140 offset1:173
	s_waitcnt lgkmcnt(0)
	v_cvt_pk_bf16_f32 v26, v26, v27
	ds_read2_b32 v[28:29], v12 offset0:206 offset1:239
	s_waitcnt lgkmcnt(0)
	v_cvt_pk_bf16_f32 v27, v28, v29
	v_or_b32_e32 v28, s4, v13
	v_ashrrev_i32_e32 v29, 31, v28
	v_lshlrev_b64 v[28:29], 11, v[28:29]
	v_lshl_add_u64 v[28:29], v[30:31], 0, v[28:29]
	ds_read2_b32 v[32:33], v12 offset0:16 offset1:49
	global_store_dwordx4 v[28:29], v[24:27], off
	s_waitcnt lgkmcnt(0)
	s_nop 0
	v_cvt_pk_bf16_f32 v24, v32, v33
	ds_read2_b32 v[26:27], v12 offset0:82 offset1:115
	s_waitcnt lgkmcnt(0)
	v_cvt_pk_bf16_f32 v25, v26, v27
	ds_read2_b32 v[26:27], v12 offset0:148 offset1:181
	s_waitcnt lgkmcnt(0)
	v_cvt_pk_bf16_f32 v26, v26, v27
	ds_read2_b32 v[28:29], v12 offset0:214 offset1:247
	s_waitcnt lgkmcnt(0)
	v_cvt_pk_bf16_f32 v27, v28, v29
	v_or_b32_e32 v28, s4, v14
	v_ashrrev_i32_e32 v29, 31, v28
	v_lshlrev_b64 v[28:29], 11, v[28:29]
	v_lshl_add_u64 v[28:29], v[30:31], 0, v[28:29]
	ds_read2_b32 v[32:33], v12 offset0:24 offset1:57
	global_store_dwordx4 v[28:29], v[24:27], off
	s_waitcnt lgkmcnt(0)
	s_nop 0
	v_cvt_pk_bf16_f32 v24, v32, v33
	ds_read2_b32 v[26:27], v12 offset0:90 offset1:123
	s_waitcnt lgkmcnt(0)
	v_cvt_pk_bf16_f32 v25, v26, v27
	ds_read2_b32 v[26:27], v12 offset0:156 offset1:189
	s_waitcnt lgkmcnt(0)
	v_cvt_pk_bf16_f32 v26, v26, v27
	ds_read2_b32 v[28:29], v12 offset0:222 offset1:255
	s_waitcnt lgkmcnt(0)
	v_cvt_pk_bf16_f32 v27, v28, v29
	v_or_b32_e32 v28, s4, v15
	v_ashrrev_i32_e32 v29, 31, v28
	v_lshlrev_b64 v[28:29], 11, v[28:29]
	v_lshl_add_u64 v[28:29], v[30:31], 0, v[28:29]
	global_store_dwordx4 v[28:29], v[24:27], off
	s_waitcnt lgkmcnt(0)
	s_branch .Lxp1_1492
.Lxp1_end:
	s_waitcnt vmcnt(0)
	s_barrier
	s_and_saveexec_b64 s[42:43], s[12:13]
	s_cbranch_execz .LBB0_1487
	s_add_i32 s4, 0, 0x20020
	v_mov_b32_e32 v0, s4
	s_waitcnt vmcnt(0) expcnt(0) lgkmcnt(0)
	ds_read_b32 v0, v0
	s_add_i32 s4, 0, 0x20024
	v_mov_b32_e32 v1, s4
	ds_read_b32 v2, v1
	s_waitcnt lgkmcnt(1)
	v_cmp_ne_u32_e32 vcc, 0, v0
	s_cbranch_vccnz .LBB0_1458
	s_mov_b64 s[4:5], 0x4200
	v_lshl_add_u64 v[0:1], v[128:129], 0, s[4:5]
	s_mov_b64 s[4:5], 0x4400
	s_waitcnt lgkmcnt(0)
	v_lshl_add_u64 v[2:3], v[128:129], 0, s[4:5]
	s_mov_b64 s[4:5], 0x4500
	s_load_dword s6, s[80:81], 0x14
	v_lshl_add_u64 v[4:5], v[128:129], 0, s[4:5]
	s_mov_b64 s[4:5], 0x4600
	v_lshl_add_u64 v[6:7], v[128:129], 0, s[4:5]
	s_mov_b64 s[4:5], 0x4700
	v_lshl_add_u64 v[8:9], v[128:129], 0, s[4:5]
	s_mov_b64 s[4:5], 0x4800
	v_lshl_add_u64 v[10:11], v[128:129], 0, s[4:5]
	s_mov_b64 s[4:5], 0x4900
	v_lshl_add_u64 v[12:13], v[128:129], 0, s[4:5]
	s_mov_b64 s[4:5], 0x4a00
	s_waitcnt lgkmcnt(0)
	s_lshr_b32 s8, s6, 16
	s_and_b32 s6, s6, 0xffff
	v_lshl_add_u64 v[14:15], v[128:129], 0, s[4:5]
	s_mov_b64 s[4:5], 0x4b00
	s_cmp_lg_u32 s6, 0
	v_lshl_add_u64 v[16:17], v[128:129], 0, s[4:5]
	s_mov_b64 s[4:5], 0x4c00
	s_cselect_b64 s[6:7], -1, 0
	v_lshl_add_u64 v[18:19], v[128:129], 0, s[4:5]
	s_mov_b64 s[4:5], 0x4d00
	s_cmp_lg_u64 s[6:7], 0
	v_lshl_add_u64 v[20:21], v[128:129], 0, s[4:5]
	s_mov_b64 s[4:5], 0x4e00
	s_addc_u32 s6, s39, 0
	v_lshl_add_u64 v[22:23], v[128:129], 0, s[4:5]
	s_mov_b64 s[4:5], 0x4f00
	s_cmp_lg_u32 s8, 0
	v_lshl_add_u64 v[24:25], v[128:129], 0, s[4:5]
	s_mov_b64 s[4:5], 0x5000
	s_mul_i32 s24, s6, s38
	s_cselect_b64 s[6:7], -1, 0
	v_lshl_add_u64 v[26:27], v[128:129], 0, s[4:5]
	s_mov_b64 s[4:5], 0x5100
	s_cmp_lg_u64 s[6:7], 0
	v_lshl_add_u64 v[28:29], v[128:129], 0, s[4:5]
	s_mov_b64 s[4:5], 0x5200
	s_addc_u32 s6, s78, 0
	v_lshl_add_u64 v[30:31], v[128:129], 0, s[4:5]
	s_mov_b64 s[4:5], 0x5300
	s_mul_i32 s24, s24, s6
	v_lshl_add_u64 v[32:33], v[128:129], 0, s[4:5]
	s_mov_b32 s25, 1
	s_mov_b64 s[4:5], 0
	s_branch .LBB0_1448

.LBB0_1721:
	v_ashrrev_i32_e32 v1, 31, v8
	v_lshrrev_b32_e32 v1, 26, v1
	v_add_u32_e32 v1, v8, v1
	v_ashrrev_i32_e32 v9, 6, v1
	v_bfe_i32 v1, v8, 27, 1
	v_lshlrev_b32_e32 v0, 4, v8
	v_lshrrev_b32_e32 v1, 22, v1
	v_add_u32_e32 v1, v0, v1
	v_and_b32_e32 v1, 0xfffffc00, v1
	v_sub_u32_e32 v1, v0, v1
	v_lshrrev_b32_e32 v2, 4, v1
	v_bitop3_b32 v2, v2, v1, 32 bitop3:0x6c
	v_ashrrev_i32_e32 v1, 31, v1
	s_ashr_i32 s5, s4, 31
	v_lshrrev_b32_e32 v1, 26, v1
	s_waitcnt lgkmcnt(0)
	s_add_u32 s8, s8, s4
	v_lshlrev_b32_e32 v3, 3, v9
	v_add_u32_e32 v1, v2, v1
	s_addc_u32 s9, s9, s5
	v_and_b32_e32 v3, 0xfffff0, v3
	v_ashrrev_i32_e32 v11, 6, v1
	s_add_u32 s43, s8, 0x4d00000
	v_add_u32_e32 v1, v11, v3
	v_lshlrev_b32_e32 v3, 5, v9
	s_addc_u32 s44, s9, 0
	v_and_b32_e32 v10, 32, v3
	v_mul_i32_i24_e32 v3, 64, v11
	s_add_u32 s45, s8, 0xb000000
	v_sub_u32_e32 v2, v2, v3
	v_mov_b32_e32 v3, 1
	s_movk_i32 s20, 0xb00
	s_addc_u32 s46, s9, 0
	v_ashrrev_i16_sdwa v2, v3, sext(v2) dst_sel:DWORD dst_unused:UNUSED_PAD src0_sel:DWORD src1_sel:BYTE_0
	v_mul_lo_u32 v1, v1, s20
	s_add_i32 s8, s14, s10
	v_bfe_i32 v12, v2, 0, 16
	v_or_b32_e32 v1, v1, v10
	v_add_u32_e32 v0, 0x2000, v0
	s_ashr_i32 s9, s8, 31
	v_add_lshl_u32 v132, v1, v12, 1
	v_ashrrev_i32_e32 v1, 31, v0
	s_lshr_b32 s9, s9, 27
	v_lshrrev_b32_e32 v1, 22, v1
	s_add_i32 s9, s8, s9
	v_add_u32_e32 v1, v0, v1
	s_ashr_i32 s10, s9, 5
	s_and_b32 s9, s9, 0xffe0
	v_ashrrev_i32_e32 v13, 10, v1
	s_sub_i32 s8, s8, s9
	v_mul_i32_i24_e32 v1, 0x400, v13
	s_bfe_i32 s9, s8, 0x80000
	v_sub_u32_e32 v0, v0, v1
	s_bfe_u32 s9, s9, 0x3000c
	v_lshrrev_b32_e32 v1, 4, v0
	s_add_i32 s9, s8, s9
	v_bitop3_b32 v0, v1, v0, 32 bitop3:0x6c
	s_bfe_i32 s11, s9, 0x80000
	s_and_b32 s9, s9, 0xf8
	v_ashrrev_i32_e32 v2, 31, v0
	s_sub_i32 s8, s8, s9
	v_lshrrev_b32_e32 v2, 26, v2
	s_lshl_b32 s10, s10, 3
	s_sext_i32_i16 s11, s11
	s_sext_i32_i8 s8, s8
	v_add_u32_e32 v2, v0, v2
	s_ashr_i32 s16, s18, 6
	s_add_i32 s64, s10, s8
	s_ashr_i32 s8, s11, 3
	s_ashr_i32 s19, s18, 8
	v_lshlrev_b32_e32 v1, 3, v13
	v_ashrrev_i32_e32 v14, 6, v2
	v_and_b32_e32 v2, 0xc0, v2
	s_lshl_b32 s47, s16, 10
	s_lshr_b32 s21, s11, 3
	s_mul_hi_i32 s9, s8, 0x160000
	s_mul_i32 s8, s8, 0x160000
	v_and_b32_e32 v1, 0xfffff0, v1
	v_sub_u32_e32 v0, v0, v2
	s_add_u32 s30, s45, s8
	v_add_u32_e32 v1, v14, v1
	v_lshlrev_b32_e32 v4, 5, v13
	v_ashrrev_i16_sdwa v0, v3, sext(v0) dst_sel:DWORD dst_unused:UNUSED_PAD src0_sel:DWORD src1_sel:BYTE_0
	s_addc_u32 s31, s46, s9
	s_add_i32 s48, s47, 0
	v_and_b32_e32 v15, 32, v4
	v_bfe_i32 v16, v0, 0, 16
	v_mul_lo_u32 v0, v1, s20
	s_add_i32 m0, s48, 0x10000
	v_or_b32_e32 v0, v0, v15
	global_load_lds_dwordx4 v132, s[30:31]
	s_add_i32 m0, s48, 0x12000
	v_add_lshl_u32 v134, v0, v16, 1
	s_add_u32 s8, s30, 0xb0000
	global_load_lds_dwordx4 v134, s[30:31]
	s_addc_u32 s9, s31, 0
	s_add_i32 m0, s48, 0x14000
	s_mul_i32 s14, s64, 0x160000
	global_load_lds_dwordx4 v132, s[8:9]
	s_add_i32 m0, s48, 0x16000
	s_mul_hi_i32 s10, s64, 0x160000
	s_add_u32 s28, s43, s14
	s_addc_u32 s29, s44, s10
	s_add_i32 s49, s48, 0x2000
	global_load_lds_dwordx4 v134, s[8:9]
	s_mov_b32 m0, s48
	s_add_u32 s8, s28, 0xb0000
	global_load_lds_dwordx4 v132, s[28:29]
	s_mov_b32 m0, s49
	s_addc_u32 s9, s29, 0
	s_add_i32 s50, s48, 0x4000
	global_load_lds_dwordx4 v134, s[28:29]
	s_mov_b32 m0, s50
	s_add_i32 s51, s48, 0x6000
	global_load_lds_dwordx4 v132, s[8:9]
	s_mov_b32 m0, s51
	v_mov_b32_e32 v133, 0
	global_load_lds_dwordx4 v134, s[8:9]
	v_mov_b32_e32 v135, v133
	s_cmp_eq_u32 s19, 1
	s_mov_b32 s52, 0
	v_lshl_add_u64 v[6:7], s[30:31], 0, v[132:133]
	v_lshl_add_u64 v[4:5], s[30:31], 0, v[134:135]
	s_mov_b64 s[8:9], 0xb0000
	v_lshl_add_u64 v[0:1], s[28:29], 0, v[132:133]
	s_cselect_b64 s[10:11], -1, 0
	s_cmp_lg_u32 s19, 1
	v_lshl_add_u64 v[2:3], s[28:29], 0, v[134:135]
	s_cbranch_scc1 .LBB0_1723
	s_barrier
